# v25: v23 with closed-form next-tile coordinates (xcd = L&7, off = L>>3) and scalar has-next test in both input-projection GEMMs
# speedup vs baseline: 1.0031x; 1.0031x over previous
.LBB0_153:
	s_add_i32 s47, s47, 1
	s_mul_i32 s3, s47, s67
	s_mul_hi_u32 s4, s47, s64
	s_add_i32 s4, s4, s3
	s_mul_i32 s3, s47, s64
	s_add_u32 s8, s3, s76
	s_addc_u32 s9, s4, s66
	s_cmp_lt_u32 s8, 0xa00
	s_cselect_b64 s[4:5], exec, 0
	s_cbranch_scc0 .LBB0_155
	s_and_b32 s3, s8, 7
	s_lshr_b32 s9, s8, 3
	s_lshl_b32 s3, s3, 3
	s_lshr_b32 s20, s9, 3
	s_and_b32 s9, s9, 7
	s_add_i32 s22, s3, s9

.LBB0_443:
	s_add_i32 s46, s46, 1
	s_mul_i32 s3, s46, s67
	s_mul_hi_u32 s6, s46, s64
	s_add_i32 s6, s6, s3
	s_mul_i32 s3, s46, s64
	s_add_u32 s24, s3, s76
	s_addc_u32 s25, s6, s66
	s_cmp_lt_u32 s24, 0xc00
	s_cselect_b64 s[6:7], exec, 0
	s_cbranch_scc0 .LBB0_445
	s_and_b32 s3, s24, 7
	s_lshr_b32 s21, s24, 3
	s_lshl_b32 s3, s3, 1
	s_cmp_ge_u32 s21, 0xc0
	s_cselect_b32 s20, 0xc0, 0
	s_cselect_b32 s22, 1, 0
	s_sub_i32 s21, s21, s20
	s_add_i32 s3, s3, s22
	s_lshl_b32 s3, s3, 3
	s_lshr_b32 s20, s21, 3
	s_and_b32 s21, s21, 7
	s_add_i32 s22, s3, s21
